# stack + streaming (nt) stores for the final f32 output tiles
# baseline (speedup 1.0000x reference)
; #define EPI_ROWS(ai, m) _Pragma("unroll") for (int ai = 0; ai < 2; ++ai) _Pragma("unroll") for (int m = 0; m < 4; ++m)
; #define EPI_FENCE() asm volatile("" ::: "memory")
; DI float rstd_of(float ssq, float invn) { return __builtin_amdgcn_rsqf(ssq * invn + EPS); }
;     DI void operator()(Acc& acc, const Unit& u, int wr, int wc, int fr, int fq) const {
;     ...
;         float rr[2][4]; f32x4 gg[2][2];
;         EPI_ROWS(ai, m) rr[ai][m] = __hip_atomic_load(ssq + epi_row(u, ai, wr, m, fr), __ATOMIC_RELAXED, __HIP_MEMORY_SCOPE_AGENT);
; #pragma unroll
;         for (int bj = 0; bj < 2; ++bj) { const int col = epi_col(u, bj, wc, fq); gg[bj][0] = *(const f32x4*)(gain + col); gg[bj][1] = *(const f32x4*)(gain + col + 4); }
;         EPI_FENCE();
;         EPI_ROWS(ai, m) { const int row = epi_row(u, ai, wr, m, fr); const float r = rstd_of(rr[ai][m], 1.0f / D);
; #pragma unroll
;             for (int bj = 0; bj < 2; ++bj) { const size_t off = (size_t)row * D + epi_col(u, bj, wc, fq);
;                 *(f32x4*)(out + off) = acc[ai][bj][m][0] * r * gg[bj][0]; *(f32x4*)(out + off + 4) = acc[ai][bj][m][1] * r * gg[bj][1]; } }
.LBB0_1557:
	s_or_b64 exec, exec, s[4:5]
	s_barrier
	global_load_dword v86, v[212:213], off sc1
	global_load_dword v87, v[214:215], off sc1
	global_load_dword v88, v[216:217], off sc1
	s_nop 0
	global_load_dword v217, v[218:219], off sc1
	s_nop 0
	global_load_dword v218, v[220:221], off sc1
	global_load_dword v219, v[96:97], off sc1
	s_nop 0
	global_load_dword v220, v[80:81], off sc1
	global_load_dword v221, v[0:1], off sc1
	v_lshl_add_u64 v[0:1], s[10:11], 0, v[194:195]
	global_load_dwordx4 v[12:15], v[0:1], off
	global_load_dwordx4 v[8:11], v[0:1], off offset:16
	global_load_dwordx4 v[4:7], v[0:1], off offset:512
	s_nop 0
	global_load_dwordx4 v[0:3], v[0:1], off offset:528
	v_lshl_add_u64 v[80:81], s[8:9], 0, v[202:203]
	v_lshl_add_u64 v[82:83], s[8:9], 0, v[200:201]
	v_lshl_add_u64 v[84:85], s[8:9], 0, v[198:199]
	v_lshl_add_u64 v[188:189], v[80:81], 0, v[194:195]
	v_lshl_add_u64 v[198:199], v[80:81], 0, v[192:193]
	v_lshl_add_u64 v[200:201], v[82:83], 0, v[194:195]
	v_lshl_add_u64 v[202:203], v[82:83], 0, v[192:193]
	v_lshl_add_u64 v[212:213], v[84:85], 0, v[194:195]
	v_lshl_add_u64 v[214:215], v[84:85], 0, v[192:193]
	s_and_b64 vcc, exec, s[0:1]
	s_mov_b64 s[0:1], -1
	s_waitcnt vmcnt(11)
	v_fmamk_f32 v80, v86, 0x3a800000, v233
	s_waitcnt vmcnt(10)
	v_fmamk_f32 v81, v87, 0x3a800000, v233
	v_rsq_f32_e32 v80, v80
	s_waitcnt vmcnt(9)
	v_fmamk_f32 v83, v88, 0x3a800000, v233
	v_rsq_f32_e32 v82, v81
	v_rsq_f32_e32 v216, v83
	v_pk_mul_f32 v[84:85], v[124:125], v[80:81] op_sel_hi:[1,0]
	v_pk_mul_f32 v[86:87], v[126:127], v[80:81] op_sel_hi:[1,0]
	v_pk_mul_f32 v[88:89], v[120:121], v[80:81] op_sel_hi:[1,0]
	v_pk_mul_f32 v[90:91], v[122:123], v[80:81] op_sel_hi:[1,0]
	v_pk_mul_f32 v[92:93], v[116:117], v[80:81] op_sel_hi:[1,0]
	v_pk_mul_f32 v[94:95], v[118:119], v[80:81] op_sel_hi:[1,0]
	v_pk_mul_f32 v[96:97], v[112:113], v[80:81] op_sel_hi:[1,0]
	v_pk_mul_f32 v[98:99], v[114:115], v[80:81] op_sel_hi:[1,0]
	v_pk_mul_f32 v[100:101], v[172:173], v[82:83] op_sel_hi:[1,0]
	v_pk_mul_f32 v[102:103], v[174:175], v[82:83] op_sel_hi:[1,0]
	v_pk_mul_f32 v[104:105], v[168:169], v[82:83] op_sel_hi:[1,0]
	v_pk_mul_f32 v[106:107], v[170:171], v[82:83] op_sel_hi:[1,0]
	v_pk_mul_f32 v[108:109], v[164:165], v[82:83] op_sel_hi:[1,0]
	v_pk_mul_f32 v[110:111], v[166:167], v[82:83] op_sel_hi:[1,0]
	v_pk_mul_f32 v[112:113], v[160:161], v[82:83] op_sel_hi:[1,0]
	v_pk_mul_f32 v[114:115], v[162:163], v[82:83] op_sel_hi:[1,0]
	s_waitcnt vmcnt(8)
	v_pk_mul_f32 v[116:117], v[156:157], v[216:217] op_sel_hi:[1,0]
	v_pk_mul_f32 v[118:119], v[158:159], v[216:217] op_sel_hi:[1,0]
	v_pk_mul_f32 v[120:121], v[152:153], v[216:217] op_sel_hi:[1,0]
	v_pk_mul_f32 v[122:123], v[154:155], v[216:217] op_sel_hi:[1,0]
	v_pk_mul_f32 v[124:125], v[206:207], v[216:217] op_sel_hi:[1,0]
	v_pk_mul_f32 v[126:127], v[204:205], v[216:217] op_sel_hi:[1,0]
	s_waitcnt vmcnt(3)
	v_pk_mul_f32 v[82:83], v[86:87], v[14:15]
	v_pk_mul_f32 v[80:81], v[84:85], v[12:13]
	s_waitcnt vmcnt(2)
	v_pk_mul_f32 v[86:87], v[90:91], v[10:11]
	v_pk_mul_f32 v[84:85], v[88:89], v[8:9]
	s_waitcnt vmcnt(1)
	v_pk_mul_f32 v[90:91], v[94:95], v[6:7]
	v_pk_mul_f32 v[88:89], v[92:93], v[4:5]
	s_waitcnt vmcnt(0)
	v_pk_mul_f32 v[94:95], v[98:99], v[2:3]
	v_pk_mul_f32 v[92:93], v[96:97], v[0:1]
	v_pk_mul_f32 v[98:99], v[14:15], v[102:103]
	v_pk_mul_f32 v[96:97], v[12:13], v[100:101]
	v_pk_mul_f32 v[102:103], v[106:107], v[10:11]
	v_pk_mul_f32 v[100:101], v[104:105], v[8:9]
	v_pk_mul_f32 v[106:107], v[110:111], v[6:7]
	v_pk_mul_f32 v[104:105], v[108:109], v[4:5]
	v_pk_mul_f32 v[110:111], v[114:115], v[2:3]
	v_pk_mul_f32 v[108:109], v[112:113], v[0:1]
	v_pk_mul_f32 v[114:115], v[14:15], v[118:119]
	v_pk_mul_f32 v[112:113], v[12:13], v[116:117]
	v_pk_mul_f32 v[118:119], v[10:11], v[122:123]
	v_pk_mul_f32 v[116:117], v[8:9], v[120:121]
	v_pk_mul_f32 v[122:123], v[126:127], v[6:7]
	v_pk_mul_f32 v[120:121], v[124:125], v[4:5]
	global_store_dwordx4 v[188:189], v[80:83], off nt
	global_store_dwordx4 v[188:189], v[84:87], off offset:16 nt
	global_store_dwordx4 v[198:199], v[88:91], off nt
	global_store_dwordx4 v[198:199], v[92:95], off offset:16 nt
	global_store_dwordx4 v[200:201], v[96:99], off nt
	global_store_dwordx4 v[200:201], v[100:103], off offset:16 nt
	global_store_dwordx4 v[202:203], v[104:107], off nt
	global_store_dwordx4 v[202:203], v[108:111], off offset:16 nt
	global_store_dwordx4 v[212:213], v[112:115], off nt
	global_store_dwordx4 v[212:213], v[116:119], off offset:16 nt
	global_store_dwordx4 v[214:215], v[120:123], off nt
	v_fmamk_f32 v82, v217, 0x3a800000, v233
	v_rsq_f32_e32 v84, v82
	v_pk_mul_f32 v[152:153], v[208:209], v[216:217] op_sel_hi:[1,0]
	v_pk_mul_f32 v[80:81], v[146:147], v[216:217] op_sel_hi:[1,0]
	v_lshl_add_u64 v[86:87], s[8:9], 0, v[196:197]
	v_pk_mul_f32 v[82:83], v[80:81], v[2:3]
	v_pk_mul_f32 v[80:81], v[152:153], v[0:1]
	global_store_dwordx4 v[214:215], v[80:83], off offset:16 nt
	v_lshl_add_u64 v[88:89], v[86:87], 0, v[194:195]
	v_lshl_add_u64 v[86:87], v[86:87], 0, v[192:193]
	v_pk_mul_f32 v[80:81], v[140:141], v[84:85] op_sel_hi:[1,0]
	v_pk_mul_f32 v[82:83], v[142:143], v[84:85] op_sel_hi:[1,0]
	v_pk_mul_f32 v[80:81], v[12:13], v[80:81]
	v_pk_mul_f32 v[82:83], v[14:15], v[82:83]
	global_store_dwordx4 v[88:89], v[80:83], off nt
	s_nop 1
	v_pk_mul_f32 v[80:81], v[136:137], v[84:85] op_sel_hi:[1,0]
	v_pk_mul_f32 v[82:83], v[138:139], v[84:85] op_sel_hi:[1,0]
	v_pk_mul_f32 v[80:81], v[8:9], v[80:81]
	v_pk_mul_f32 v[82:83], v[10:11], v[82:83]
	global_store_dwordx4 v[88:89], v[80:83], off offset:16 nt
	s_nop 1
; #define EPI_ROWS(ai, m) _Pragma("unroll") for (int ai = 0; ai < 2; ++ai) _Pragma("unroll") for (int m = 0; m < 4; ++m)
; DI float rstd_of(float ssq, float invn) { return __builtin_amdgcn_rsqf(ssq * invn + EPS); }
;     DI void operator()(Acc& acc, const Unit& u, int wr, int wc, int fr, int fq) const {
;     ...
;         EPI_ROWS(ai, m) { const int row = epi_row(u, ai, wr, m, fr); const float r = rstd_of(rr[ai][m], 1.0f / D);
; #pragma unroll
;             for (int bj = 0; bj < 2; ++bj) { const size_t off = (size_t)row * D + epi_col(u, bj, wc, fq);
;                 *(f32x4*)(out + off) = acc[ai][bj][m][0] * r * gg[bj][0]; *(f32x4*)(out + off + 4) = acc[ai][bj][m][1] * r * gg[bj][1]; } }
	v_pk_mul_f32 v[80:81], v[150:151], v[84:85] op_sel_hi:[1,0]
	v_pk_mul_f32 v[82:83], v[144:145], v[84:85] op_sel_hi:[1,0]
	v_pk_mul_f32 v[80:81], v[4:5], v[80:81]
	v_pk_mul_f32 v[82:83], v[6:7], v[82:83]
	global_store_dwordx4 v[86:87], v[80:83], off nt
	s_nop 1
	v_pk_mul_f32 v[80:81], v[148:149], v[84:85] op_sel_hi:[1,0]
	v_pk_mul_f32 v[82:83], v[132:133], v[84:85] op_sel_hi:[1,0]
	v_fmamk_f32 v84, v218, 0x3a800000, v233
	v_rsq_f32_e32 v84, v84
	v_pk_mul_f32 v[82:83], v[82:83], v[2:3]
	v_pk_mul_f32 v[80:81], v[80:81], v[0:1]
	global_store_dwordx4 v[86:87], v[80:83], off offset:16 nt
	v_pk_mul_f32 v[56:57], v[56:57], v[84:85] op_sel_hi:[1,0]
	v_pk_mul_f32 v[58:59], v[58:59], v[84:85] op_sel_hi:[1,0]
	v_lshl_add_u64 v[80:81], s[8:9], 0, v[210:211]
	v_lshl_add_u64 v[82:83], v[80:81], 0, v[194:195]
	v_pk_mul_f32 v[58:59], v[10:11], v[58:59]
	v_pk_mul_f32 v[56:57], v[8:9], v[56:57]
	v_pk_mul_f32 v[52:53], v[52:53], v[84:85] op_sel_hi:[1,0]
	v_pk_mul_f32 v[54:55], v[54:55], v[84:85] op_sel_hi:[1,0]
	global_store_dwordx4 v[82:83], v[56:59], off offset:16 nt
	v_pk_mul_f32 v[54:55], v[6:7], v[54:55]
	v_pk_mul_f32 v[52:53], v[4:5], v[52:53]
	v_lshl_add_u64 v[56:57], v[80:81], 0, v[192:193]
	global_store_dwordx4 v[56:57], v[52:55], off nt
	v_pk_mul_f32 v[48:49], v[48:49], v[84:85] op_sel_hi:[1,0]
	v_pk_mul_f32 v[50:51], v[50:51], v[84:85] op_sel_hi:[1,0]
	v_fmamk_f32 v52, v219, 0x3a800000, v233
	v_rsq_f32_e32 v52, v52
	v_pk_mul_f32 v[50:51], v[2:3], v[50:51]
	v_pk_mul_f32 v[48:49], v[0:1], v[48:49]
	global_store_dwordx4 v[56:57], v[48:51], off offset:16 nt
	v_pk_mul_f32 v[40:41], v[40:41], v[52:53] op_sel_hi:[1,0]
	v_pk_mul_f32 v[42:43], v[42:43], v[52:53] op_sel_hi:[1,0]
	v_lshl_add_u64 v[48:49], s[8:9], 0, v[134:135]
	v_pk_mul_f32 v[60:61], v[60:61], v[84:85] op_sel_hi:[1,0]
	v_pk_mul_f32 v[62:63], v[62:63], v[84:85] op_sel_hi:[1,0]
	v_lshl_add_u64 v[50:51], v[48:49], 0, v[194:195]
	v_pk_mul_f32 v[42:43], v[10:11], v[42:43]
	v_pk_mul_f32 v[40:41], v[8:9], v[40:41]
	v_pk_mul_f32 v[36:37], v[36:37], v[52:53] op_sel_hi:[1,0]
	v_pk_mul_f32 v[38:39], v[38:39], v[52:53] op_sel_hi:[1,0]
	v_pk_mul_f32 v[62:63], v[14:15], v[62:63]
	v_pk_mul_f32 v[60:61], v[12:13], v[60:61]
	global_store_dwordx4 v[50:51], v[40:43], off offset:16 nt
	v_pk_mul_f32 v[38:39], v[6:7], v[38:39]
	v_pk_mul_f32 v[36:37], v[4:5], v[36:37]
	v_lshl_add_u64 v[40:41], v[48:49], 0, v[192:193]
	global_store_dwordx4 v[82:83], v[60:63], off nt
	global_store_dwordx4 v[40:41], v[36:39], off nt
	v_pk_mul_f32 v[32:33], v[32:33], v[52:53] op_sel_hi:[1,0]
	v_pk_mul_f32 v[34:35], v[34:35], v[52:53] op_sel_hi:[1,0]
	v_fmamk_f32 v36, v220, 0x3a800000, v233
	v_rsq_f32_e32 v36, v36
	v_pk_mul_f32 v[34:35], v[2:3], v[34:35]
	v_pk_mul_f32 v[32:33], v[0:1], v[32:33]
	global_store_dwordx4 v[40:41], v[32:35], off offset:16 nt
	v_pk_mul_f32 v[24:25], v[24:25], v[36:37] op_sel_hi:[1,0]
	v_pk_mul_f32 v[26:27], v[26:27], v[36:37] op_sel_hi:[1,0]
	v_lshl_add_u64 v[32:33], s[8:9], 0, v[130:131]
	v_pk_mul_f32 v[44:45], v[44:45], v[52:53] op_sel_hi:[1,0]
	v_pk_mul_f32 v[46:47], v[46:47], v[52:53] op_sel_hi:[1,0]
	v_lshl_add_u64 v[34:35], v[32:33], 0, v[194:195]
	v_pk_mul_f32 v[26:27], v[10:11], v[26:27]
	v_pk_mul_f32 v[24:25], v[8:9], v[24:25]
	v_pk_mul_f32 v[20:21], v[20:21], v[36:37] op_sel_hi:[1,0]
	v_pk_mul_f32 v[22:23], v[22:23], v[36:37] op_sel_hi:[1,0]
	v_pk_mul_f32 v[46:47], v[14:15], v[46:47]
	v_pk_mul_f32 v[44:45], v[12:13], v[44:45]
	global_store_dwordx4 v[34:35], v[24:27], off offset:16 nt
	v_pk_mul_f32 v[22:23], v[6:7], v[22:23]
	v_pk_mul_f32 v[20:21], v[4:5], v[20:21]
	v_lshl_add_u64 v[24:25], v[32:33], 0, v[192:193]
	global_store_dwordx4 v[50:51], v[44:47], off nt
	global_store_dwordx4 v[24:25], v[20:23], off nt
	v_pk_mul_f32 v[16:17], v[16:17], v[36:37] op_sel_hi:[1,0]
	v_pk_mul_f32 v[18:19], v[18:19], v[36:37] op_sel_hi:[1,0]
	v_fmamk_f32 v20, v221, 0x3a800000, v233
	v_rsq_f32_e32 v20, v20
	v_pk_mul_f32 v[18:19], v[2:3], v[18:19]
	v_pk_mul_f32 v[16:17], v[0:1], v[16:17]
	v_pk_mul_f32 v[28:29], v[28:29], v[36:37] op_sel_hi:[1,0]
	global_store_dwordx4 v[24:25], v[16:19], off offset:16 nt
	v_pk_mul_f32 v[30:31], v[30:31], v[36:37] op_sel_hi:[1,0]
	v_pk_mul_f32 v[28:29], v[12:13], v[28:29]
	v_pk_mul_f32 v[16:17], v[76:77], v[20:21] op_sel_hi:[1,0]
	v_pk_mul_f32 v[18:19], v[78:79], v[20:21] op_sel_hi:[1,0]
	v_pk_mul_f32 v[12:13], v[12:13], v[16:17]
	v_lshl_add_u64 v[16:17], s[8:9], 0, v[128:129]
	v_pk_mul_f32 v[30:31], v[14:15], v[30:31]
	v_pk_mul_f32 v[14:15], v[14:15], v[18:19]
	v_lshl_add_u64 v[18:19], v[16:17], 0, v[194:195]
	global_store_dwordx4 v[18:19], v[12:15], off nt
	global_store_dwordx4 v[34:35], v[28:31], off nt
	s_nop 0
	v_pk_mul_f32 v[12:13], v[72:73], v[20:21] op_sel_hi:[1,0]
	v_pk_mul_f32 v[14:15], v[74:75], v[20:21] op_sel_hi:[1,0]
	v_pk_mul_f32 v[8:9], v[8:9], v[12:13]
	v_pk_mul_f32 v[10:11], v[10:11], v[14:15]
	global_store_dwordx4 v[18:19], v[8:11], off offset:16 nt
	s_nop 1
	v_pk_mul_f32 v[8:9], v[68:69], v[20:21] op_sel_hi:[1,0]
	v_pk_mul_f32 v[10:11], v[70:71], v[20:21] op_sel_hi:[1,0]
	v_pk_mul_f32 v[4:5], v[4:5], v[8:9]
	v_pk_mul_f32 v[6:7], v[6:7], v[10:11]
	v_lshl_add_u64 v[8:9], v[16:17], 0, v[192:193]
	global_store_dwordx4 v[8:9], v[4:7], off nt
	s_nop 1
	v_pk_mul_f32 v[4:5], v[64:65], v[20:21] op_sel_hi:[1,0]
	v_pk_mul_f32 v[6:7], v[66:67], v[20:21] op_sel_hi:[1,0]
	v_pk_mul_f32 v[0:1], v[0:1], v[4:5]
	v_pk_mul_f32 v[2:3], v[2:3], v[6:7]
	global_store_dwordx4 v[8:9], v[0:3], off offset:16 nt
	s_cbranch_vccnz .LBB0_1514
	s_andn2_b64 vcc, exec, s[6:7]
	s_cbranch_vccnz .LBB0_1513
	s_barrier
	s_branch .LBB0_1513
